# attention unit prologue: counted wait vmcnt(6) (Q + tile 0) before the first barrier, tile 1 waited at the end of tile 0
# baseline (speedup 1.0000x reference)
.Lam_go:
	s_bfe_u32 s14, s46, 0x10001
	s_lshl_b32 s15, s12, 9
	s_lshl_b32 s28, s14, 8
	s_add_i32 s28, s28, s15
	s_lshl_b32 s8, s10, 12
	s_add_i32 s8, s8, s28
	s_add_u32 s16, s40, s8
	s_addc_u32 s17, s41, 0
	s_lshl_b32 s8, s11, 12
	s_add_i32 s9, s8, s28
	s_add_u32 s18, s42, s9
	s_addc_u32 s19, s43, 0
	s_add_i32 s9, s8, s15
	s_add_u32 s20, s44, s9
	s_addc_u32 s21, s45, 0
	s_lshl_b32 s8, s10, 13
	s_lshl_b32 s9, s28, 1
	s_add_i32 s8, s8, s9
	s_add_u32 s22, s48, s8
	s_addc_u32 s23, s49, 0
	v_mbcnt_lo_u32_b32 v96, -1, 0
	v_mbcnt_hi_u32_b32 v96, -1, v96
	s_lshr_b32 s36, s84, 6
	s_lshl_b32 s38, s36, 3
	s_lshl_b32 s39, s36, 11
	s_lshl_b32 s47, s36, 12
	s_add_i32 s47, s47, 0x4000
	s_lshl_b32 s50, s36, 8
	s_add_i32 s50, s50, 0x18000
	v_and_b32_e32 v240, 31, v96
	v_lshrrev_b32_e32 v241, 5, v96
	s_lshl_b32 s37, s36, 5
	v_add_u32_e32 v242, s37, v240
	v_lshlrev_b32_e32 v242, 12, v242
	v_lshl_add_u32 v242, v241, 4, v242
	global_load_dwordx4 v[130:133], v242, s[16:17]
	global_load_dwordx4 v[134:137], v242, s[16:17] offset:32
	global_load_dwordx4 v[138:141], v242, s[16:17] offset:64
	global_load_dwordx4 v[142:145], v242, s[16:17] offset:96
	global_load_dwordx4 v[146:149], v242, s[16:17] offset:128
	global_load_dwordx4 v[150:153], v242, s[16:17] offset:160
	global_load_dwordx4 v[154:157], v242, s[16:17] offset:192
	global_load_dwordx4 v[158:161], v242, s[16:17] offset:224
	v_lshlrev_b32_e32 v243, 8, v240
	v_and_b32_e32 v238, 7, v240
	v_lshlrev_b32_e32 v238, 4, v238
	v_lshlrev_b32_e32 v239, 4, v241
	v_mov_b32_e32 v228, v239
	v_xor_b32_e32 v228, v228, v238
	v_add_u32_e32 v228, v228, v243
	v_or_b32_e32 v229, 32, v239
	v_xor_b32_e32 v229, v229, v238
	v_add_u32_e32 v229, v229, v243
	v_or_b32_e32 v230, 64, v239
	v_xor_b32_e32 v230, v230, v238
	v_add_u32_e32 v230, v230, v243
	v_or_b32_e32 v231, 96, v239
	v_xor_b32_e32 v231, v231, v238
	v_add_u32_e32 v231, v231, v243
	v_or_b32_e32 v232, 128, v239
	v_xor_b32_e32 v232, v232, v238
	v_add_u32_e32 v232, v232, v243
	v_or_b32_e32 v233, 160, v239
	v_xor_b32_e32 v233, v233, v238
	v_add_u32_e32 v233, v233, v243
	v_or_b32_e32 v234, 192, v239
	v_xor_b32_e32 v234, v234, v238
	v_add_u32_e32 v234, v234, v243
	v_or_b32_e32 v235, 224, v239
	v_xor_b32_e32 v235, v235, v238
	v_add_u32_e32 v235, v235, v243
	v_and_b32_e32 v238, 3, v96
	v_lshlrev_b32_e32 v236, 3, v238
	v_bfe_u32 v238, v96, 2, 2
	v_lshl_or_b32 v236, v238, 6, v236
	v_bfe_u32 v238, v96, 4, 1
	v_lshl_or_b32 v236, v238, 5, v236
	v_lshl_or_b32 v236, v241, 8, v236
	v_add_u32_e32 v237, 0x10000, v236
	v_add_u32_e32 v236, 0x4000, v236
	v_lshrrev_b32_e32 v238, 4, v96
	v_and_b32_e32 v239, 15, v96
	v_add_u32_e32 v243, 0, v238
	v_xor_b32_e32 v244, v239, v243
	v_lshlrev_b32_e32 v244, 4, v244
	v_add_u32_e32 v243, s38, v243
	v_lshl_add_u32 v244, v243, 12, v244
	v_add_u32_e32 v243, 4, v238
	v_xor_b32_e32 v245, v239, v243
	v_lshlrev_b32_e32 v245, 4, v245
	v_add_u32_e32 v243, s38, v243
	v_lshl_add_u32 v245, v243, 12, v245
	v_lshrrev_b32_e32 v238, 2, v240
	v_add_u32_e32 v238, s38, v238
	v_and_b32_e32 v239, 0xfffffff3, v238
	v_and_b32_e32 v243, 4, v238
	v_lshl_or_b32 v239, v243, 1, v239
	v_and_b32_e32 v243, 8, v238
	v_lshrrev_b32_e32 v243, 1, v243
	v_or_b32_e32 v239, v239, v243
	v_lshlrev_b32_e32 v239, 12, v239
	v_and_b32_e32 v238, 3, v240
	v_lshlrev_b32_e32 v238, 4, v238
	v_add_u32_e32 v243, 0, v241
	v_lshl_add_u32 v243, v243, 6, v238
	v_add_u32_e32 v246, v239, v243
	v_add_u32_e32 v243, 2, v241
	v_lshl_add_u32 v243, v243, 6, v238
	v_add_u32_e32 v247, v239, v243
	v_add_u32_e32 v243, 4, v241
	v_lshl_add_u32 v243, v243, 6, v238
	v_add_u32_e32 v248, v239, v243
	v_add_u32_e32 v243, 6, v241
	v_lshl_add_u32 v243, v243, 6, v238
	v_add_u32_e32 v249, v239, v243
	v_mov_b32_e32 v238, 0xf149f2ca
	v_mov_b32_e32 v239, 0
	v_mov_b32_e32 v0, 0
	v_mov_b32_e32 v1, 0
	v_mov_b32_e32 v2, 0
	v_mov_b32_e32 v3, 0
	v_mov_b32_e32 v4, 0
	v_mov_b32_e32 v5, 0
	v_mov_b32_e32 v6, 0
	v_mov_b32_e32 v7, 0
	v_mov_b32_e32 v8, 0
	v_mov_b32_e32 v9, 0
	v_mov_b32_e32 v10, 0
	v_mov_b32_e32 v11, 0
	v_mov_b32_e32 v12, 0
	v_mov_b32_e32 v13, 0
	v_mov_b32_e32 v14, 0
	v_mov_b32_e32 v15, 0
	v_mov_b32_e32 v16, 0
	v_mov_b32_e32 v17, 0
	v_mov_b32_e32 v18, 0
	v_mov_b32_e32 v19, 0
	v_mov_b32_e32 v20, 0
	v_mov_b32_e32 v21, 0
	v_mov_b32_e32 v22, 0
	v_mov_b32_e32 v23, 0
	v_mov_b32_e32 v24, 0
	v_mov_b32_e32 v25, 0
	v_mov_b32_e32 v26, 0
	v_mov_b32_e32 v27, 0
	v_mov_b32_e32 v28, 0
	v_mov_b32_e32 v29, 0
	v_mov_b32_e32 v30, 0
	v_mov_b32_e32 v31, 0
	v_mov_b32_e32 v32, 0
	v_mov_b32_e32 v33, 0
	v_mov_b32_e32 v34, 0
	v_mov_b32_e32 v35, 0
	v_mov_b32_e32 v36, 0
	v_mov_b32_e32 v37, 0
	v_mov_b32_e32 v38, 0
	v_mov_b32_e32 v39, 0
	v_mov_b32_e32 v40, 0
	v_mov_b32_e32 v41, 0
	v_mov_b32_e32 v42, 0
	v_mov_b32_e32 v43, 0
	v_mov_b32_e32 v44, 0
	v_mov_b32_e32 v45, 0
	v_mov_b32_e32 v46, 0
	v_mov_b32_e32 v47, 0
	v_mov_b32_e32 v48, 0
	v_mov_b32_e32 v49, 0
	v_mov_b32_e32 v50, 0
	v_mov_b32_e32 v51, 0
	v_mov_b32_e32 v52, 0
	v_mov_b32_e32 v53, 0
	v_mov_b32_e32 v54, 0
	v_mov_b32_e32 v55, 0
	v_mov_b32_e32 v56, 0
	v_mov_b32_e32 v57, 0
	v_mov_b32_e32 v58, 0
	v_mov_b32_e32 v59, 0
	v_mov_b32_e32 v60, 0
	v_mov_b32_e32 v61, 0
	v_mov_b32_e32 v62, 0
	v_mov_b32_e32 v63, 0
	v_mov_b32_e32 v64, 0
	v_mov_b32_e32 v65, 0
	v_mov_b32_e32 v66, 0
	v_mov_b32_e32 v67, 0
	v_mov_b32_e32 v68, 0
	v_mov_b32_e32 v69, 0
	v_mov_b32_e32 v70, 0
	v_mov_b32_e32 v71, 0
	v_mov_b32_e32 v72, 0
	v_mov_b32_e32 v73, 0
	v_mov_b32_e32 v74, 0
	v_mov_b32_e32 v75, 0
	v_mov_b32_e32 v76, 0
	v_mov_b32_e32 v77, 0
	v_mov_b32_e32 v78, 0
	v_mov_b32_e32 v79, 0
	v_mov_b32_e32 v80, 0
	v_mov_b32_e32 v81, 0
	v_mov_b32_e32 v82, 0
	v_mov_b32_e32 v83, 0
	v_mov_b32_e32 v84, 0
	v_mov_b32_e32 v85, 0
	v_mov_b32_e32 v86, 0
	v_mov_b32_e32 v87, 0
	v_mov_b32_e32 v88, 0
	v_mov_b32_e32 v89, 0
	v_mov_b32_e32 v90, 0
	v_mov_b32_e32 v91, 0
	v_mov_b32_e32 v92, 0
	v_mov_b32_e32 v93, 0
	v_mov_b32_e32 v94, 0
	v_mov_b32_e32 v95, 0
	v_mov_b32_e32 v98, 0
	v_mov_b32_e32 v99, 0
	v_mov_b32_e32 v100, 0
	v_mov_b32_e32 v101, 0
	v_mov_b32_e32 v102, 0
	v_mov_b32_e32 v103, 0
	v_mov_b32_e32 v104, 0
	v_mov_b32_e32 v105, 0
	v_mov_b32_e32 v106, 0
	v_mov_b32_e32 v107, 0
	v_mov_b32_e32 v108, 0
	v_mov_b32_e32 v109, 0
	v_mov_b32_e32 v110, 0
	v_mov_b32_e32 v111, 0
	v_mov_b32_e32 v112, 0
	v_mov_b32_e32 v113, 0
	v_mov_b32_e32 v114, 0
	v_mov_b32_e32 v115, 0
	v_mov_b32_e32 v116, 0
	v_mov_b32_e32 v117, 0
	v_mov_b32_e32 v118, 0
	v_mov_b32_e32 v119, 0
	v_mov_b32_e32 v120, 0
	v_mov_b32_e32 v121, 0
	v_mov_b32_e32 v122, 0
	v_mov_b32_e32 v123, 0
	v_mov_b32_e32 v124, 0
	v_mov_b32_e32 v125, 0
	v_mov_b32_e32 v126, 0
	v_mov_b32_e32 v127, 0
	v_mov_b32_e32 v128, 0
	v_mov_b32_e32 v129, 0
	s_add_i32 m0, s39, 0x0
	s_nop 0
	global_load_lds_dwordx4 v244, s[18:19]
	s_add_i32 m0, s39, 0x400
	s_nop 0
	global_load_lds_dwordx4 v245, s[18:19]
	s_add_i32 m0, s47, 0x0
	s_nop 0
	global_load_lds_dwordx4 v246, s[20:21]
	s_add_i32 m0, s47, 0x400
	s_nop 0
	global_load_lds_dwordx4 v247, s[20:21]
	s_add_i32 m0, s47, 0x800
	s_nop 0
	global_load_lds_dwordx4 v248, s[20:21]
	s_add_i32 m0, s47, 0xc00
	s_nop 0
	global_load_lds_dwordx4 v249, s[20:21]
	s_add_u32 s18, s18, 0x40000
	s_addc_u32 s19, s19, 0
	s_add_u32 s20, s20, 0x40000
	s_addc_u32 s21, s21, 0
	s_add_i32 m0, s39, 0xc000
	s_nop 0
	global_load_lds_dwordx4 v244, s[18:19]
	s_add_i32 m0, s39, 0xc400
	s_nop 0
	global_load_lds_dwordx4 v245, s[18:19]
	s_add_i32 m0, s47, 0xc000
	s_nop 0
	global_load_lds_dwordx4 v246, s[20:21]
	s_add_i32 m0, s47, 0xc400
	s_nop 0
	global_load_lds_dwordx4 v247, s[20:21]
	s_add_i32 m0, s47, 0xc800
	s_nop 0
	global_load_lds_dwordx4 v248, s[20:21]
	s_add_i32 m0, s47, 0xcc00
	s_nop 0
	global_load_lds_dwordx4 v249, s[20:21]
	s_add_u32 s18, s18, 0x40000
	s_addc_u32 s19, s19, 0
	s_add_u32 s20, s20, 0x40000
	s_addc_u32 s21, s21, 0
	s_waitcnt vmcnt(6)
	s_barrier
